# attention: first V fragment reads issued in the post-QK MFMA-to-VALU wait slot
# speedup vs baseline: 1.0155x; 1.0155x over previous
; #define ATT_WV(n, x) asm volatile("s_waitcnt lgkmcnt(" #n ")" : "+v"(x) :: "memory")
; __device__ __forceinline__ void attn_phase(LAS unsigned char* ldsb, bf16_t* P, const bf16_t* Kn, const bf16_t* KPE, const bf16_t* VT) {
;     ...
;                     float ps = 0.f;
; #pragma unroll
;                     for (int kb = 0; kb < 2; ++kb)
; #pragma unroll
;                         for (int i = 0; i < 16; ++i) { const float p = __builtin_amdgcn_exp2f(st[kb][i] - mrun); st[kb][i] = p; ps += p; }
;                     lrun += ps;
;                     bf16x8 pb[2][2];
; #pragma unroll
;                     for (int kb = 0; kb < 2; ++kb)
; #pragma unroll
;                         for (int s2 = 0; s2 < 2; ++s2) {
;                             u32x4 pw; pw.x = pk2(st[kb][8 * s2 + 0], st[kb][8 * s2 + 1]); pw.y = pk2(st[kb][8 * s2 + 2], st[kb][8 * s2 + 3]);
;                             pw.z = pk2(st[kb][8 * s2 + 4], st[kb][8 * s2 + 5]); pw.w = pk2(st[kb][8 * s2 + 6], st[kb][8 * s2 + 7]);
;                             pb[kb][s2] = __builtin_bit_cast(bf16x8, pw); }
;                     {
;                         const unsigned va0 = (unsigned)(size_t)(sVt + r * 68 + 4 * hh), va1 = va0 + 32 * 68 * 2, va2 = va0 + 64 * 68 * 2, va3 = va0 + 96 * 68 * 2;
;                         bf16x8 vfa, vfb;
;     ...
;                         ATT_RV(vfa, va0, 0, 2);
;                         ATT_RV(vfb, va1, 0, 2); ATT_WV(1, vfa); o[0] = __builtin_amdgcn_mfma_f32_32x32x16_bf16(vfa, pb[0][0], o[0], 0, 0, 0);
;                         ATT_RV(vfa, va2, 0, 2); ATT_WV(1, vfb); o[1] = __builtin_amdgcn_mfma_f32_32x32x16_bf16(vfb, pb[0][0], o[1], 0, 0, 0);
;                         ATT_RV(vfb, va3, 0, 2); ATT_WV(1, vfa); o[2] = __builtin_amdgcn_mfma_f32_32x32x16_bf16(vfa, pb[0][0], o[2], 0, 0, 0);
;                         ATT_RV(vfa, va0, 4, 6); ATT_WV(1, vfb); o[3] = __builtin_amdgcn_mfma_f32_32x32x16_bf16(vfb, pb[0][0], o[3], 0, 0, 0);
;                         ATT_RV(vfb, va1, 4, 6); ATT_WV(1, vfa); o[0] = __builtin_amdgcn_mfma_f32_32x32x16_bf16(vfa, pb[0][1], o[0], 0, 0, 0);
;                         ATT_RV(vfa, va2, 4, 6); ATT_WV(1, vfb); o[1] = __builtin_amdgcn_mfma_f32_32x32x16_bf16(vfb, pb[0][1], o[1], 0, 0, 0);
;                         ATT_RV(vfb, va3, 4, 6); ATT_WV(1, vfa); o[2] = __builtin_amdgcn_mfma_f32_32x32x16_bf16(vfa, pb[0][1], o[2], 0, 0, 0);
.LBB0_1525:
	v_sub_f32_e32 v96, v96, v240
	v_sub_f32_e32 v97, v97, v240
	v_exp_f32_e32 v96, v96
	v_sub_f32_e32 v98, v98, v240
	v_exp_f32_e32 v97, v97
	v_sub_f32_e32 v99, v99, v240
	v_exp_f32_e32 v98, v98
	v_add_f32_e32 v0, 0, v96
	v_exp_f32_e32 v99, v99
	v_sub_f32_e32 v100, v100, v240
	v_add_f32_e32 v0, v97, v0
	v_sub_f32_e32 v101, v101, v240
	v_exp_f32_e32 v100, v100
	v_cvt_pk_bf16_f32 v2, v96, v97
	v_add_f32_e32 v0, v98, v0
	v_exp_f32_e32 v101, v101
	v_sub_f32_e32 v102, v102, v240
	v_add_f32_e32 v0, v99, v0
	v_sub_f32_e32 v103, v103, v240
	v_exp_f32_e32 v102, v102
	v_cvt_pk_bf16_f32 v3, v98, v99
	v_exp_f32_e32 v103, v103
	v_add_f32_e32 v0, v100, v0
	v_add_f32_e32 v0, v101, v0
	v_cvt_pk_bf16_f32 v4, v100, v101
	v_add_f32_e32 v0, v102, v0
	v_cvt_pk_bf16_f32 v5, v102, v103
	v_add_f32_e32 v0, v103, v0
	s_waitcnt lgkmcnt(7)
	v_mfma_f32_32x32x16_bf16 v[64:79], v[154:157], v[2:5], v[64:79]
	ds_read2_b64 v[154:157], v239 offset0:8 offset1:10
	v_sub_f32_e32 v104, v104, v240
	v_sub_f32_e32 v105, v105, v240
	v_exp_f32_e32 v104, v104
	v_sub_f32_e32 v106, v106, v240
	v_exp_f32_e32 v105, v105
	v_sub_f32_e32 v107, v107, v240
	v_exp_f32_e32 v106, v106
	s_waitcnt lgkmcnt(7)
	v_mfma_f32_32x32x16_bf16 v[48:63], v[158:161], v[2:5], v[48:63]
	ds_read2_b64 v[158:161], v238 offset0:8 offset1:10
	v_add_f32_e32 v0, v104, v0
	v_exp_f32_e32 v107, v107
	v_sub_f32_e32 v108, v108, v240
	v_add_f32_e32 v0, v105, v0
	v_sub_f32_e32 v109, v109, v240
	v_exp_f32_e32 v108, v108
	v_cvt_pk_bf16_f32 v6, v104, v105
	s_waitcnt lgkmcnt(7)
	v_mfma_f32_32x32x16_bf16 v[32:47], v[162:165], v[2:5], v[32:47]
	ds_read2_b64 v[162:165], v237 offset0:8 offset1:10
	v_add_f32_e32 v0, v106, v0
	v_exp_f32_e32 v109, v109
	v_sub_f32_e32 v110, v110, v240
	v_add_f32_e32 v0, v107, v0
	v_sub_f32_e32 v111, v111, v240
	v_exp_f32_e32 v110, v110
	v_cvt_pk_bf16_f32 v7, v106, v107
	s_waitcnt lgkmcnt(7)
	v_mfma_f32_32x32x16_bf16 v[16:31], v[166:169], v[2:5], v[16:31]
	ds_read2_b64 v[166:169], v235 offset0:8 offset1:10
	v_exp_f32_e32 v111, v111
	v_add_f32_e32 v0, v108, v0
	v_add_f32_e32 v0, v109, v0
	v_cvt_pk_bf16_f32 v8, v108, v109
	v_add_f32_e32 v0, v110, v0
	v_cvt_pk_bf16_f32 v9, v110, v111
	v_add_f32_e32 v0, v111, v0
	s_waitcnt lgkmcnt(7)
	v_mfma_f32_32x32x16_bf16 v[64:79], v[170:173], v[6:9], v[64:79]
	ds_read2_b64 v[170:173], v239 offset0:12 offset1:14
	v_sub_f32_e32 v80, v80, v240
	v_sub_f32_e32 v81, v81, v240
	v_exp_f32_e32 v80, v80
	v_sub_f32_e32 v82, v82, v240
	v_exp_f32_e32 v81, v81
	v_sub_f32_e32 v83, v83, v240
	v_exp_f32_e32 v82, v82
	s_waitcnt lgkmcnt(7)
	v_mfma_f32_32x32x16_bf16 v[48:63], v[244:247], v[6:9], v[48:63]
	ds_read2_b64 v[244:247], v238 offset0:12 offset1:14
	v_add_f32_e32 v0, v80, v0
	v_exp_f32_e32 v83, v83
	v_sub_f32_e32 v84, v84, v240
	v_add_f32_e32 v0, v81, v0
	v_sub_f32_e32 v85, v85, v240
	v_exp_f32_e32 v84, v84
	v_cvt_pk_bf16_f32 v10, v80, v81
	s_waitcnt lgkmcnt(7)
	v_mfma_f32_32x32x16_bf16 v[32:47], v[248:251], v[6:9], v[32:47]
	ds_read2_b64 v[248:251], v237 offset0:12 offset1:14
	v_add_f32_e32 v0, v82, v0
	v_exp_f32_e32 v85, v85
	v_sub_f32_e32 v86, v86, v240
	v_add_f32_e32 v0, v83, v0
	v_sub_f32_e32 v87, v87, v240
	v_exp_f32_e32 v86, v86
	v_cvt_pk_bf16_f32 v11, v82, v83
	s_waitcnt lgkmcnt(7)
	v_mfma_f32_32x32x16_bf16 v[16:31], v[252:255], v[6:9], v[16:31]
	ds_read2_b64 v[252:255], v235 offset0:12 offset1:14
	v_exp_f32_e32 v87, v87
	v_add_f32_e32 v0, v84, v0
	v_add_f32_e32 v0, v85, v0
	v_cvt_pk_bf16_f32 v12, v84, v85
	v_add_f32_e32 v0, v86, v0
	v_cvt_pk_bf16_f32 v13, v86, v87
	v_add_f32_e32 v0, v87, v0
	s_waitcnt lgkmcnt(7)
	v_mfma_f32_32x32x16_bf16 v[64:79], v[154:157], v[10:13], v[64:79]
	v_sub_f32_e32 v88, v88, v240
	v_sub_f32_e32 v89, v89, v240
	v_exp_f32_e32 v88, v88
	v_sub_f32_e32 v90, v90, v240
	v_exp_f32_e32 v89, v89
	v_sub_f32_e32 v91, v91, v240
	v_exp_f32_e32 v90, v90
	s_waitcnt lgkmcnt(6)
	v_mfma_f32_32x32x16_bf16 v[48:63], v[158:161], v[10:13], v[48:63]
	v_add_f32_e32 v0, v88, v0
	v_exp_f32_e32 v91, v91
	v_sub_f32_e32 v92, v92, v240
	v_add_f32_e32 v0, v89, v0
	v_sub_f32_e32 v93, v93, v240
	v_exp_f32_e32 v92, v92
	v_cvt_pk_bf16_f32 v96, v88, v89
	s_waitcnt lgkmcnt(5)
	v_mfma_f32_32x32x16_bf16 v[32:47], v[162:165], v[10:13], v[32:47]
	v_add_f32_e32 v0, v90, v0
	v_exp_f32_e32 v93, v93
	v_sub_f32_e32 v94, v94, v240
	v_add_f32_e32 v0, v91, v0
	v_sub_f32_e32 v95, v95, v240
	v_exp_f32_e32 v94, v94
	v_cvt_pk_bf16_f32 v97, v90, v91
	s_waitcnt lgkmcnt(4)
	v_mfma_f32_32x32x16_bf16 v[16:31], v[166:169], v[10:13], v[16:31]
	v_exp_f32_e32 v95, v95
	v_add_f32_e32 v0, v92, v0
	v_add_f32_e32 v0, v93, v0
	v_cvt_pk_bf16_f32 v98, v92, v93
	v_add_f32_e32 v0, v94, v0
	v_cvt_pk_bf16_f32 v99, v94, v95
	v_add_f32_e32 v0, v95, v0
	s_waitcnt lgkmcnt(3)
	v_mfma_f32_32x32x16_bf16 v[64:79], v[170:173], v[96:99], v[64:79]
	v_add_f32_e32 v236, v236, v0
	s_waitcnt lgkmcnt(2)
	v_mfma_f32_32x32x16_bf16 v[48:63], v[244:247], v[96:99], v[48:63]
	s_waitcnt lgkmcnt(1)
	v_mfma_f32_32x32x16_bf16 v[32:47], v[248:251], v[96:99], v[32:47]
	s_waitcnt lgkmcnt(0)
	v_mfma_f32_32x32x16_bf16 v[16:31], v[252:255], v[96:99], v[16:31]

; DI unsigned pk2(float a, float b) { f32x2 v = {a, b}; bf16v2 r = __builtin_convertvector(v, bf16v2); return __builtin_bit_cast(unsigned, r); }
; #define ATT_RV(dst, va, o0, o1) asm volatile("ds_read2_b64 %0, %1 offset0:" #o0 " offset1:" #o1 : "=&v"(dst) : "v"(va) : "memory")
; __device__ __forceinline__ void attn_phase(LAS unsigned char* ldsb, bf16_t* P, const bf16_t* Kn, const bf16_t* KPE, const bf16_t* VT) {
;     ...
;                     float mx = st[0][0];
; #pragma unroll
;                     for (int kb = 0; kb < 2; ++kb)
; #pragma unroll
;                         for (int i = 0; i < 16; ++i) mx = fmaxf(mx, st[kb][i]);
;                     mx = fmaxf(mx, __shfl_xor(mx, 32));
;                     if (__builtin_amdgcn_ballot_w64(mx > mrun) != 0ull) {
;                         const float mnew = fmaxf(mrun, mx);
;                         const float alpha = __builtin_amdgcn_exp2f(mrun - mnew);
;                         mrun = mnew; lrun *= alpha;
; #pragma unroll
;                         for (int d = 0; d < 4; ++d)
; #pragma unroll
;                             for (int i = 0; i < 16; ++i) o[d][i] *= alpha;
;                     }
;                     float ps = 0.f;
; #pragma unroll
;                     for (int kb = 0; kb < 2; ++kb)
; #pragma unroll
;                         for (int i = 0; i < 16; ++i) { const float p = __builtin_amdgcn_exp2f(st[kb][i] - mrun); st[kb][i] = p; ps += p; }
;                     lrun += ps;
;                     bf16x8 pb[2][2];
; #pragma unroll
;                     for (int kb = 0; kb < 2; ++kb)
; #pragma unroll
;                         for (int s2 = 0; s2 < 2; ++s2) {
;                             u32x4 pw; pw.x = pk2(st[kb][8 * s2 + 0], st[kb][8 * s2 + 1]); pw.y = pk2(st[kb][8 * s2 + 2], st[kb][8 * s2 + 3]);
;                             pw.z = pk2(st[kb][8 * s2 + 4], st[kb][8 * s2 + 5]); pw.w = pk2(st[kb][8 * s2 + 6], st[kb][8 * s2 + 7]);
;                             pb[kb][s2] = __builtin_bit_cast(bf16x8, pw); }
;                     {
;                         const unsigned va0 = (unsigned)(size_t)(sVt + r * 68 + 4 * hh), va1 = va0 + 32 * 68 * 2, va2 = va0 + 64 * 68 * 2, va3 = va0 + 96 * 68 * 2;
;                         bf16x8 vfa, vfb;
;     ...
;                         ATT_RV(vfa, va0, 0, 2);
.LBB0_1530:
	ds_read2_b64 v[154:157], v239 offset0:0 offset1:2
	ds_read2_b64 v[158:161], v238 offset0:0 offset1:2
	ds_read2_b64 v[162:165], v237 offset0:0 offset1:2
	ds_read2_b64 v[166:169], v235 offset0:0 offset1:2
	ds_read2_b64 v[170:173], v239 offset0:4 offset1:6
	ds_read2_b64 v[244:247], v238 offset0:4 offset1:6
	ds_read2_b64 v[248:251], v237 offset0:4 offset1:6
	ds_read2_b64 v[252:255], v235 offset0:4 offset1:6
	s_nop 1
	v_max_f32_e32 v0, v97, v97
	v_max_f32_e32 v2, v96, v96
	v_max_f32_e32 v0, v2, v0
	v_max3_f32 v0, v0, v98, v99
	v_max3_f32 v0, v0, v100, v101
	v_max3_f32 v0, v0, v102, v103
	v_max3_f32 v0, v0, v104, v105
	v_max3_f32 v0, v0, v106, v107
	v_max3_f32 v0, v0, v108, v109
	v_max3_f32 v0, v0, v110, v111
	v_max3_f32 v0, v0, v80, v81
	v_max3_f32 v0, v0, v82, v83
	v_max3_f32 v0, v0, v84, v85
	v_max3_f32 v0, v0, v86, v87
	v_and_b32_e32 v3, 64, v234
	v_max3_f32 v0, v0, v88, v89
	v_xor_b32_e32 v2, 32, v234
	v_add_u32_e32 v3, 64, v3
	v_max3_f32 v0, v0, v90, v91
	v_cmp_lt_i32_e32 vcc, v2, v3
	v_max3_f32 v0, v0, v92, v93
	v_max3_f32 v0, v0, v94, v95
	v_cndmask_b32_e32 v2, v234, v2, vcc
	v_lshlrev_b32_e32 v2, 2, v2
	ds_bpermute_b32 v2, v2, v0
	s_waitcnt lgkmcnt(0)
	v_max_f32_e32 v2, v2, v2
	v_max_f32_e32 v0, v0, v2
	v_sub_f32_e32 v2, v0, v240
	v_cmp_lt_f32_e32 vcc, 4.0, v2
	s_cbranch_vccz .LBB0_1525
	v_max_f32_e32 v0, v0, v0
	v_max_f32_e32 v2, v240, v240
	v_max_f32_e32 v2, v2, v0
	v_sub_f32_e32 v0, v240, v2
	v_exp_f32_e32 v0, v0
	v_mov_b32_e32 v240, v2
	v_pk_mul_f32 v[78:79], v[78:79], v[0:1] op_sel_hi:[1,0]
	v_pk_mul_f32 v[76:77], v[76:77], v[0:1] op_sel_hi:[1,0]
	v_pk_mul_f32 v[74:75], v[74:75], v[0:1] op_sel_hi:[1,0]
	v_pk_mul_f32 v[72:73], v[72:73], v[0:1] op_sel_hi:[1,0]
	v_pk_mul_f32 v[70:71], v[70:71], v[0:1] op_sel_hi:[1,0]
	v_pk_mul_f32 v[68:69], v[68:69], v[0:1] op_sel_hi:[1,0]
	v_pk_mul_f32 v[66:67], v[66:67], v[0:1] op_sel_hi:[1,0]
	v_pk_mul_f32 v[64:65], v[64:65], v[0:1] op_sel_hi:[1,0]
	v_pk_mul_f32 v[62:63], v[62:63], v[0:1] op_sel_hi:[1,0]
	v_pk_mul_f32 v[60:61], v[60:61], v[0:1] op_sel_hi:[1,0]
	v_pk_mul_f32 v[58:59], v[58:59], v[0:1] op_sel_hi:[1,0]
	v_pk_mul_f32 v[56:57], v[56:57], v[0:1] op_sel_hi:[1,0]
	v_pk_mul_f32 v[54:55], v[54:55], v[0:1] op_sel_hi:[1,0]
	v_pk_mul_f32 v[52:53], v[52:53], v[0:1] op_sel_hi:[1,0]
	v_pk_mul_f32 v[50:51], v[50:51], v[0:1] op_sel_hi:[1,0]
	v_pk_mul_f32 v[48:49], v[48:49], v[0:1] op_sel_hi:[1,0]
	v_pk_mul_f32 v[46:47], v[46:47], v[0:1] op_sel_hi:[1,0]
	v_pk_mul_f32 v[44:45], v[44:45], v[0:1] op_sel_hi:[1,0]
	v_pk_mul_f32 v[42:43], v[42:43], v[0:1] op_sel_hi:[1,0]
	v_pk_mul_f32 v[40:41], v[40:41], v[0:1] op_sel_hi:[1,0]
	v_pk_mul_f32 v[38:39], v[38:39], v[0:1] op_sel_hi:[1,0]
	v_pk_mul_f32 v[36:37], v[36:37], v[0:1] op_sel_hi:[1,0]
	v_pk_mul_f32 v[34:35], v[34:35], v[0:1] op_sel_hi:[1,0]
	v_pk_mul_f32 v[32:33], v[32:33], v[0:1] op_sel_hi:[1,0]
	v_pk_mul_f32 v[30:31], v[30:31], v[0:1] op_sel_hi:[1,0]
	v_pk_mul_f32 v[28:29], v[28:29], v[0:1] op_sel_hi:[1,0]
	v_pk_mul_f32 v[26:27], v[26:27], v[0:1] op_sel_hi:[1,0]
	v_pk_mul_f32 v[24:25], v[24:25], v[0:1] op_sel_hi:[1,0]
	v_pk_mul_f32 v[22:23], v[22:23], v[0:1] op_sel_hi:[1,0]
	v_pk_mul_f32 v[20:21], v[20:21], v[0:1] op_sel_hi:[1,0]
	v_pk_mul_f32 v[18:19], v[18:19], v[0:1] op_sel_hi:[1,0]
	v_pk_mul_f32 v[16:17], v[16:17], v[0:1] op_sel_hi:[1,0]
	v_mul_f32_e32 v236, v236, v0
	s_branch .LBB0_1525
